# P8 hid stores widened: fq lane pairs exchange halves with v_permlane16_swap so each row is one 16-byte write-through (sc1) store per lane instead of two 8-byte stores
# baseline (speedup 1.0000x reference)
.Lp8_nonext:
	v_lshl_add_u32 v214, s8, 8, v146
	v_lshl_or_b32 v215, s0, 7, v148
	v_mul_u32_u24_e32 v154, 0x1600, v214
	v_lshl_add_u32 v154, v215, 1, v154
	v_bfe_u32 v216, v254, 4, 1
	v_mul_u32_u24_e32 v216, 0x78, v216
	v_add_u32_e32 v154, v154, v216
	v_add_u32_e32 v155, 0x16000, v154
	v_add_u32_e32 v156, 0x2c000, v154
	v_add_u32_e32 v157, 0x42000, v154
	v_add_u32_e32 v158, 0xb0000, v154
	v_add_u32_e32 v159, 0xc6000, v154
	v_add_u32_e32 v160, 0xdc000, v154
	v_add_u32_e32 v161, 0xf2000, v154
	s_waitcnt lgkmcnt(0)
	v_add_f32_e32 v174, v174, v175
	v_add_f32_e32 v178, v178, v179
	v_add_f32_e32 v182, v182, v183
	v_add_f32_e32 v186, v186, v187
	v_add_f32_e32 v190, v190, v191
	v_add_f32_e32 v194, v194, v195
	v_add_f32_e32 v198, v198, v199
	v_add_f32_e32 v202, v202, v203
	v_add_f32_e32 v174, v174, v176
	v_add_f32_e32 v178, v178, v180
	v_add_f32_e32 v182, v182, v184
	v_add_f32_e32 v186, v186, v188
	v_add_f32_e32 v190, v190, v192
	v_add_f32_e32 v194, v194, v196
	v_add_f32_e32 v198, v198, v200
	v_add_f32_e32 v202, v202, v204
	v_add_f32_e32 v174, v174, v177
	v_add_f32_e32 v178, v178, v181
	v_add_f32_e32 v182, v182, v185
	v_add_f32_e32 v186, v186, v189
	v_add_f32_e32 v190, v190, v193
	v_add_f32_e32 v194, v194, v197
	v_add_f32_e32 v198, v198, v201
	v_add_f32_e32 v202, v202, v205
	v_fmamk_f32 v174, v174, 0x3a800000, v152
	v_fmamk_f32 v178, v178, 0x3a800000, v152
	v_fmamk_f32 v182, v182, 0x3a800000, v152
	v_fmamk_f32 v186, v186, 0x3a800000, v152
	v_fmamk_f32 v190, v190, 0x3a800000, v152
	v_fmamk_f32 v194, v194, 0x3a800000, v152
	v_fmamk_f32 v198, v198, 0x3a800000, v152
	v_fmamk_f32 v202, v202, 0x3a800000, v152
	v_mul_f32_e32 v175, 0x4b800000, v174
	v_mul_f32_e32 v179, 0x4b800000, v178
	v_mul_f32_e32 v183, 0x4b800000, v182
	v_mul_f32_e32 v187, 0x4b800000, v186
	v_mul_f32_e32 v191, 0x4b800000, v190
	v_mul_f32_e32 v195, 0x4b800000, v194
	v_mul_f32_e32 v199, 0x4b800000, v198
	v_mul_f32_e32 v203, 0x4b800000, v202
	v_cmp_gt_f32_e64 s[74:75], s58, v174
	v_cmp_gt_f32_e64 s[76:77], s58, v178
	v_cmp_gt_f32_e64 s[78:79], s58, v182
	v_cmp_gt_f32_e64 s[80:81], s58, v186
	v_cmp_gt_f32_e64 s[82:83], s58, v190
	v_cmp_gt_f32_e64 s[84:85], s58, v194
	v_cmp_gt_f32_e64 s[86:87], s58, v198
	v_cmp_gt_f32_e64 s[88:89], s58, v202
	v_cndmask_b32_e64 v174, v174, v175, s[74:75]
	v_cndmask_b32_e64 v178, v178, v179, s[76:77]
	v_cndmask_b32_e64 v182, v182, v183, s[78:79]
	v_cndmask_b32_e64 v186, v186, v187, s[80:81]
	v_cndmask_b32_e64 v190, v190, v191, s[82:83]
	v_cndmask_b32_e64 v194, v194, v195, s[84:85]
	v_cndmask_b32_e64 v198, v198, v199, s[86:87]
	v_cndmask_b32_e64 v202, v202, v203, s[88:89]
	v_rsq_f32_e32 v174, v174
	v_rsq_f32_e32 v178, v178
	v_rsq_f32_e32 v182, v182
	v_rsq_f32_e32 v186, v186
	v_rsq_f32_e32 v190, v190
	v_rsq_f32_e32 v194, v194
	v_rsq_f32_e32 v198, v198
	v_rsq_f32_e32 v202, v202
	v_mul_f32_e32 v175, 0x45800000, v174
	v_mul_f32_e32 v179, 0x45800000, v178
	v_mul_f32_e32 v183, 0x45800000, v182
	v_mul_f32_e32 v187, 0x45800000, v186
	v_mul_f32_e32 v191, 0x45800000, v190
	v_mul_f32_e32 v195, 0x45800000, v194
	v_mul_f32_e32 v199, 0x45800000, v198
	v_mul_f32_e32 v203, 0x45800000, v202
	v_cndmask_b32_e64 v206, v174, v175, s[74:75]
	v_cndmask_b32_e64 v207, v178, v179, s[76:77]
	v_cndmask_b32_e64 v208, v182, v183, s[78:79]
	v_cndmask_b32_e64 v209, v186, v187, s[80:81]
	v_cndmask_b32_e64 v210, v190, v191, s[82:83]
	v_cndmask_b32_e64 v211, v194, v195, s[84:85]
	v_cndmask_b32_e64 v212, v198, v199, s[86:87]
	v_cndmask_b32_e64 v213, v202, v203, s[88:89]
	s_mov_b32 s90, 0xbfb8aa3b
	v_pk_mul_f32 v[120:121], v[120:121], v[206:207] op_sel_hi:[1,0]
	v_pk_mul_f32 v[122:123], v[122:123], v[206:207] op_sel_hi:[1,0]
	v_pk_mul_f32 v[116:117], v[116:117], v[206:207] op_sel_hi:[1,0]
	v_pk_mul_f32 v[118:119], v[118:119], v[206:207] op_sel_hi:[1,0]
	v_pk_mul_f32 v[124:125], v[124:125], v[206:207] op_sel_hi:[1,0]
	v_pk_mul_f32 v[126:127], v[126:127], v[206:207] op_sel_hi:[1,0]
	v_pk_mul_f32 v[112:113], v[112:113], v[206:207] op_sel_hi:[1,0]
	v_pk_mul_f32 v[114:115], v[114:115], v[206:207] op_sel_hi:[1,0]
	v_pk_mul_f32 v[174:175], v[120:121], s[90:91] op_sel_hi:[1,0]
	v_pk_mul_f32 v[176:177], v[122:123], s[90:91] op_sel_hi:[1,0]
	v_pk_mul_f32 v[178:179], v[116:117], s[90:91] op_sel_hi:[1,0]
	v_pk_mul_f32 v[180:181], v[118:119], s[90:91] op_sel_hi:[1,0]
	v_exp_f32_e32 v174, v174
	v_exp_f32_e32 v175, v175
	v_exp_f32_e32 v176, v176
	v_exp_f32_e32 v177, v177
	v_exp_f32_e32 v178, v178
	v_exp_f32_e32 v179, v179
	v_exp_f32_e32 v180, v180
	v_exp_f32_e32 v181, v181
	v_pk_add_f32 v[174:175], v[174:175], 1.0 op_sel_hi:[1,0]
	v_pk_add_f32 v[176:177], v[176:177], 1.0 op_sel_hi:[1,0]
	v_pk_add_f32 v[178:179], v[178:179], 1.0 op_sel_hi:[1,0]
	v_pk_add_f32 v[180:181], v[180:181], 1.0 op_sel_hi:[1,0]
	v_rcp_f32_e32 v174, v174
	v_rcp_f32_e32 v175, v175
	v_rcp_f32_e32 v176, v176
	v_rcp_f32_e32 v177, v177
	v_rcp_f32_e32 v178, v178
	v_rcp_f32_e32 v179, v179
	v_rcp_f32_e32 v180, v180
	v_rcp_f32_e32 v181, v181
	v_pk_mul_f32 v[120:121], v[120:121], v[174:175]
	v_pk_mul_f32 v[122:123], v[122:123], v[176:177]
	v_pk_mul_f32 v[116:117], v[116:117], v[178:179]
	v_pk_mul_f32 v[118:119], v[118:119], v[180:181]
	v_pk_mul_f32 v[120:121], v[124:125], v[120:121]
	v_pk_mul_f32 v[122:123], v[126:127], v[122:123]
	v_pk_mul_f32 v[116:117], v[112:113], v[116:117]
	v_pk_mul_f32 v[118:119], v[114:115], v[118:119]
	v_cvt_pk_bf16_f32 v120, v120, v121
	v_cvt_pk_bf16_f32 v121, v122, v123
	v_cvt_pk_bf16_f32 v122, v116, v117
	v_cvt_pk_bf16_f32 v123, v118, v119
	s_nop 1
	v_permlane16_swap_b32 v120, v122
	v_permlane16_swap_b32 v121, v123
	global_store_dwordx4 v154, v[120:123], s[34:35] sc1
	v_pk_mul_f32 v[108:109], v[108:109], v[206:207] op_sel:[0,1] op_sel_hi:[1,1]
	v_pk_mul_f32 v[110:111], v[110:111], v[206:207] op_sel:[0,1] op_sel_hi:[1,1]
	v_pk_mul_f32 v[100:101], v[100:101], v[206:207] op_sel:[0,1] op_sel_hi:[1,1]
	v_pk_mul_f32 v[102:103], v[102:103], v[206:207] op_sel:[0,1] op_sel_hi:[1,1]
	v_pk_mul_f32 v[104:105], v[104:105], v[206:207] op_sel:[0,1] op_sel_hi:[1,1]
	v_pk_mul_f32 v[106:107], v[106:107], v[206:207] op_sel:[0,1] op_sel_hi:[1,1]
	v_pk_mul_f32 v[96:97], v[96:97], v[206:207] op_sel:[0,1] op_sel_hi:[1,1]
	v_pk_mul_f32 v[98:99], v[98:99], v[206:207] op_sel:[0,1] op_sel_hi:[1,1]
	v_pk_mul_f32 v[174:175], v[108:109], s[90:91] op_sel_hi:[1,0]
	v_pk_mul_f32 v[176:177], v[110:111], s[90:91] op_sel_hi:[1,0]
	v_pk_mul_f32 v[178:179], v[100:101], s[90:91] op_sel_hi:[1,0]
	v_pk_mul_f32 v[180:181], v[102:103], s[90:91] op_sel_hi:[1,0]
	v_exp_f32_e32 v174, v174
	v_exp_f32_e32 v175, v175
	v_exp_f32_e32 v176, v176
	v_exp_f32_e32 v177, v177
	v_exp_f32_e32 v178, v178
	v_exp_f32_e32 v179, v179
	v_exp_f32_e32 v180, v180
	v_exp_f32_e32 v181, v181
	v_pk_add_f32 v[174:175], v[174:175], 1.0 op_sel_hi:[1,0]
	v_pk_add_f32 v[176:177], v[176:177], 1.0 op_sel_hi:[1,0]
	v_pk_add_f32 v[178:179], v[178:179], 1.0 op_sel_hi:[1,0]
	v_pk_add_f32 v[180:181], v[180:181], 1.0 op_sel_hi:[1,0]
	v_rcp_f32_e32 v174, v174
	v_rcp_f32_e32 v175, v175
	v_rcp_f32_e32 v176, v176
	v_rcp_f32_e32 v177, v177
	v_rcp_f32_e32 v178, v178
	v_rcp_f32_e32 v179, v179
	v_rcp_f32_e32 v180, v180
	v_rcp_f32_e32 v181, v181
	v_pk_mul_f32 v[108:109], v[108:109], v[174:175]
	v_pk_mul_f32 v[110:111], v[110:111], v[176:177]
	v_pk_mul_f32 v[100:101], v[100:101], v[178:179]
	v_pk_mul_f32 v[102:103], v[102:103], v[180:181]
	v_pk_mul_f32 v[108:109], v[104:105], v[108:109]
	v_pk_mul_f32 v[110:111], v[106:107], v[110:111]
	v_pk_mul_f32 v[100:101], v[96:97], v[100:101]
	v_pk_mul_f32 v[102:103], v[98:99], v[102:103]
	v_cvt_pk_bf16_f32 v108, v108, v109
	v_cvt_pk_bf16_f32 v109, v110, v111
	v_cvt_pk_bf16_f32 v110, v100, v101
	v_cvt_pk_bf16_f32 v111, v102, v103
	s_nop 1
	v_permlane16_swap_b32 v108, v110
	v_permlane16_swap_b32 v109, v111
	global_store_dwordx4 v155, v[108:111], s[34:35] sc1
	v_pk_mul_f32 v[92:93], v[92:93], v[208:209] op_sel_hi:[1,0]
	v_pk_mul_f32 v[94:95], v[94:95], v[208:209] op_sel_hi:[1,0]
	v_pk_mul_f32 v[84:85], v[84:85], v[208:209] op_sel_hi:[1,0]
	v_pk_mul_f32 v[86:87], v[86:87], v[208:209] op_sel_hi:[1,0]
	v_pk_mul_f32 v[88:89], v[88:89], v[208:209] op_sel_hi:[1,0]
	v_pk_mul_f32 v[90:91], v[90:91], v[208:209] op_sel_hi:[1,0]
	v_pk_mul_f32 v[80:81], v[80:81], v[208:209] op_sel_hi:[1,0]
	v_pk_mul_f32 v[82:83], v[82:83], v[208:209] op_sel_hi:[1,0]
	v_pk_mul_f32 v[174:175], v[92:93], s[90:91] op_sel_hi:[1,0]
	v_pk_mul_f32 v[176:177], v[94:95], s[90:91] op_sel_hi:[1,0]
	v_pk_mul_f32 v[178:179], v[84:85], s[90:91] op_sel_hi:[1,0]
	v_pk_mul_f32 v[180:181], v[86:87], s[90:91] op_sel_hi:[1,0]
	v_exp_f32_e32 v174, v174
	v_exp_f32_e32 v175, v175
	v_exp_f32_e32 v176, v176
	v_exp_f32_e32 v177, v177
	v_exp_f32_e32 v178, v178
	v_exp_f32_e32 v179, v179
	v_exp_f32_e32 v180, v180
	v_exp_f32_e32 v181, v181
	v_pk_add_f32 v[174:175], v[174:175], 1.0 op_sel_hi:[1,0]
	v_pk_add_f32 v[176:177], v[176:177], 1.0 op_sel_hi:[1,0]
	v_pk_add_f32 v[178:179], v[178:179], 1.0 op_sel_hi:[1,0]
	v_pk_add_f32 v[180:181], v[180:181], 1.0 op_sel_hi:[1,0]
	v_rcp_f32_e32 v174, v174
	v_rcp_f32_e32 v175, v175
	v_rcp_f32_e32 v176, v176
	v_rcp_f32_e32 v177, v177
	v_rcp_f32_e32 v178, v178
	v_rcp_f32_e32 v179, v179
	v_rcp_f32_e32 v180, v180
	v_rcp_f32_e32 v181, v181
	v_pk_mul_f32 v[92:93], v[92:93], v[174:175]
	v_pk_mul_f32 v[94:95], v[94:95], v[176:177]
	v_pk_mul_f32 v[84:85], v[84:85], v[178:179]
	v_pk_mul_f32 v[86:87], v[86:87], v[180:181]
	v_pk_mul_f32 v[92:93], v[88:89], v[92:93]
	v_pk_mul_f32 v[94:95], v[90:91], v[94:95]
	v_pk_mul_f32 v[84:85], v[80:81], v[84:85]
	v_pk_mul_f32 v[86:87], v[82:83], v[86:87]
	v_cvt_pk_bf16_f32 v92, v92, v93
	v_cvt_pk_bf16_f32 v93, v94, v95
	v_cvt_pk_bf16_f32 v94, v84, v85
	v_cvt_pk_bf16_f32 v95, v86, v87
	s_nop 1
	v_permlane16_swap_b32 v92, v94
	v_permlane16_swap_b32 v93, v95
	global_store_dwordx4 v156, v[92:95], s[34:35] sc1
	v_pk_mul_f32 v[76:77], v[76:77], v[208:209] op_sel:[0,1] op_sel_hi:[1,1]
	v_pk_mul_f32 v[78:79], v[78:79], v[208:209] op_sel:[0,1] op_sel_hi:[1,1]
	v_pk_mul_f32 v[68:69], v[68:69], v[208:209] op_sel:[0,1] op_sel_hi:[1,1]
	v_pk_mul_f32 v[70:71], v[70:71], v[208:209] op_sel:[0,1] op_sel_hi:[1,1]
	v_pk_mul_f32 v[72:73], v[72:73], v[208:209] op_sel:[0,1] op_sel_hi:[1,1]
	v_pk_mul_f32 v[74:75], v[74:75], v[208:209] op_sel:[0,1] op_sel_hi:[1,1]
	v_pk_mul_f32 v[64:65], v[64:65], v[208:209] op_sel:[0,1] op_sel_hi:[1,1]
	v_pk_mul_f32 v[66:67], v[66:67], v[208:209] op_sel:[0,1] op_sel_hi:[1,1]
	v_pk_mul_f32 v[174:175], v[76:77], s[90:91] op_sel_hi:[1,0]
	v_pk_mul_f32 v[176:177], v[78:79], s[90:91] op_sel_hi:[1,0]
	v_pk_mul_f32 v[178:179], v[68:69], s[90:91] op_sel_hi:[1,0]
	v_pk_mul_f32 v[180:181], v[70:71], s[90:91] op_sel_hi:[1,0]
	v_exp_f32_e32 v174, v174
	v_exp_f32_e32 v175, v175
	v_exp_f32_e32 v176, v176
	v_exp_f32_e32 v177, v177
	v_exp_f32_e32 v178, v178
	v_exp_f32_e32 v179, v179
	v_exp_f32_e32 v180, v180
	v_exp_f32_e32 v181, v181
	v_pk_add_f32 v[174:175], v[174:175], 1.0 op_sel_hi:[1,0]
	v_pk_add_f32 v[176:177], v[176:177], 1.0 op_sel_hi:[1,0]
	v_pk_add_f32 v[178:179], v[178:179], 1.0 op_sel_hi:[1,0]
	v_pk_add_f32 v[180:181], v[180:181], 1.0 op_sel_hi:[1,0]
	v_rcp_f32_e32 v174, v174
	v_rcp_f32_e32 v175, v175
	v_rcp_f32_e32 v176, v176
	v_rcp_f32_e32 v177, v177
	v_rcp_f32_e32 v178, v178
	v_rcp_f32_e32 v179, v179
	v_rcp_f32_e32 v180, v180
	v_rcp_f32_e32 v181, v181
	v_pk_mul_f32 v[76:77], v[76:77], v[174:175]
	v_pk_mul_f32 v[78:79], v[78:79], v[176:177]
	v_pk_mul_f32 v[68:69], v[68:69], v[178:179]
	v_pk_mul_f32 v[70:71], v[70:71], v[180:181]
	v_pk_mul_f32 v[76:77], v[72:73], v[76:77]
	v_pk_mul_f32 v[78:79], v[74:75], v[78:79]
	v_pk_mul_f32 v[68:69], v[64:65], v[68:69]
	v_pk_mul_f32 v[70:71], v[66:67], v[70:71]
	v_cvt_pk_bf16_f32 v76, v76, v77
	v_cvt_pk_bf16_f32 v77, v78, v79
	v_cvt_pk_bf16_f32 v78, v68, v69
	v_cvt_pk_bf16_f32 v79, v70, v71
	s_nop 1
	v_permlane16_swap_b32 v76, v78
	v_permlane16_swap_b32 v77, v79
	global_store_dwordx4 v157, v[76:79], s[34:35] sc1
	v_pk_mul_f32 v[60:61], v[60:61], v[210:211] op_sel_hi:[1,0]
	v_pk_mul_f32 v[62:63], v[62:63], v[210:211] op_sel_hi:[1,0]
	v_pk_mul_f32 v[52:53], v[52:53], v[210:211] op_sel_hi:[1,0]
	v_pk_mul_f32 v[54:55], v[54:55], v[210:211] op_sel_hi:[1,0]
	v_pk_mul_f32 v[56:57], v[56:57], v[210:211] op_sel_hi:[1,0]
	v_pk_mul_f32 v[58:59], v[58:59], v[210:211] op_sel_hi:[1,0]
	v_pk_mul_f32 v[48:49], v[48:49], v[210:211] op_sel_hi:[1,0]
	v_pk_mul_f32 v[50:51], v[50:51], v[210:211] op_sel_hi:[1,0]
	v_pk_mul_f32 v[174:175], v[60:61], s[90:91] op_sel_hi:[1,0]
	v_pk_mul_f32 v[176:177], v[62:63], s[90:91] op_sel_hi:[1,0]
	v_pk_mul_f32 v[178:179], v[52:53], s[90:91] op_sel_hi:[1,0]
	v_pk_mul_f32 v[180:181], v[54:55], s[90:91] op_sel_hi:[1,0]
	v_exp_f32_e32 v174, v174
	v_exp_f32_e32 v175, v175
	v_exp_f32_e32 v176, v176
	v_exp_f32_e32 v177, v177
	v_exp_f32_e32 v178, v178
	v_exp_f32_e32 v179, v179
	v_exp_f32_e32 v180, v180
	v_exp_f32_e32 v181, v181
	v_pk_add_f32 v[174:175], v[174:175], 1.0 op_sel_hi:[1,0]
	v_pk_add_f32 v[176:177], v[176:177], 1.0 op_sel_hi:[1,0]
	v_pk_add_f32 v[178:179], v[178:179], 1.0 op_sel_hi:[1,0]
	v_pk_add_f32 v[180:181], v[180:181], 1.0 op_sel_hi:[1,0]
	v_rcp_f32_e32 v174, v174
	v_rcp_f32_e32 v175, v175
	v_rcp_f32_e32 v176, v176
	v_rcp_f32_e32 v177, v177
	v_rcp_f32_e32 v178, v178
	v_rcp_f32_e32 v179, v179
	v_rcp_f32_e32 v180, v180
	v_rcp_f32_e32 v181, v181
	v_pk_mul_f32 v[60:61], v[60:61], v[174:175]
	v_pk_mul_f32 v[62:63], v[62:63], v[176:177]
	v_pk_mul_f32 v[52:53], v[52:53], v[178:179]
	v_pk_mul_f32 v[54:55], v[54:55], v[180:181]
	v_pk_mul_f32 v[60:61], v[56:57], v[60:61]
	v_pk_mul_f32 v[62:63], v[58:59], v[62:63]
	v_pk_mul_f32 v[52:53], v[48:49], v[52:53]
	v_pk_mul_f32 v[54:55], v[50:51], v[54:55]
	v_cvt_pk_bf16_f32 v60, v60, v61
	v_cvt_pk_bf16_f32 v61, v62, v63
	v_cvt_pk_bf16_f32 v62, v52, v53
	v_cvt_pk_bf16_f32 v63, v54, v55
	s_nop 1
	v_permlane16_swap_b32 v60, v62
	v_permlane16_swap_b32 v61, v63
	global_store_dwordx4 v158, v[60:63], s[34:35] sc1
	v_pk_mul_f32 v[44:45], v[44:45], v[210:211] op_sel:[0,1] op_sel_hi:[1,1]
	v_pk_mul_f32 v[46:47], v[46:47], v[210:211] op_sel:[0,1] op_sel_hi:[1,1]
	v_pk_mul_f32 v[36:37], v[36:37], v[210:211] op_sel:[0,1] op_sel_hi:[1,1]
	v_pk_mul_f32 v[38:39], v[38:39], v[210:211] op_sel:[0,1] op_sel_hi:[1,1]
	v_pk_mul_f32 v[40:41], v[40:41], v[210:211] op_sel:[0,1] op_sel_hi:[1,1]
	v_pk_mul_f32 v[42:43], v[42:43], v[210:211] op_sel:[0,1] op_sel_hi:[1,1]
	v_pk_mul_f32 v[32:33], v[32:33], v[210:211] op_sel:[0,1] op_sel_hi:[1,1]
	v_pk_mul_f32 v[34:35], v[34:35], v[210:211] op_sel:[0,1] op_sel_hi:[1,1]
	v_pk_mul_f32 v[174:175], v[44:45], s[90:91] op_sel_hi:[1,0]
	v_pk_mul_f32 v[176:177], v[46:47], s[90:91] op_sel_hi:[1,0]
	v_pk_mul_f32 v[178:179], v[36:37], s[90:91] op_sel_hi:[1,0]
	v_pk_mul_f32 v[180:181], v[38:39], s[90:91] op_sel_hi:[1,0]
	v_exp_f32_e32 v174, v174
	v_exp_f32_e32 v175, v175
	v_exp_f32_e32 v176, v176
	v_exp_f32_e32 v177, v177
	v_exp_f32_e32 v178, v178
	v_exp_f32_e32 v179, v179
	v_exp_f32_e32 v180, v180
	v_exp_f32_e32 v181, v181
	v_pk_add_f32 v[174:175], v[174:175], 1.0 op_sel_hi:[1,0]
	v_pk_add_f32 v[176:177], v[176:177], 1.0 op_sel_hi:[1,0]
	v_pk_add_f32 v[178:179], v[178:179], 1.0 op_sel_hi:[1,0]
	v_pk_add_f32 v[180:181], v[180:181], 1.0 op_sel_hi:[1,0]
	v_rcp_f32_e32 v174, v174
	v_rcp_f32_e32 v175, v175
	v_rcp_f32_e32 v176, v176
	v_rcp_f32_e32 v177, v177
	v_rcp_f32_e32 v178, v178
	v_rcp_f32_e32 v179, v179
	v_rcp_f32_e32 v180, v180
	v_rcp_f32_e32 v181, v181
	v_pk_mul_f32 v[44:45], v[44:45], v[174:175]
	v_pk_mul_f32 v[46:47], v[46:47], v[176:177]
	v_pk_mul_f32 v[36:37], v[36:37], v[178:179]
	v_pk_mul_f32 v[38:39], v[38:39], v[180:181]
	v_pk_mul_f32 v[44:45], v[40:41], v[44:45]
	v_pk_mul_f32 v[46:47], v[42:43], v[46:47]
	v_pk_mul_f32 v[36:37], v[32:33], v[36:37]
	v_pk_mul_f32 v[38:39], v[34:35], v[38:39]
	v_cvt_pk_bf16_f32 v44, v44, v45
	v_cvt_pk_bf16_f32 v45, v46, v47
	v_cvt_pk_bf16_f32 v46, v36, v37
	v_cvt_pk_bf16_f32 v47, v38, v39
	s_nop 1
	v_permlane16_swap_b32 v44, v46
	v_permlane16_swap_b32 v45, v47
	global_store_dwordx4 v159, v[44:47], s[34:35] sc1
	v_pk_mul_f32 v[28:29], v[28:29], v[212:213] op_sel_hi:[1,0]
	v_pk_mul_f32 v[30:31], v[30:31], v[212:213] op_sel_hi:[1,0]
	v_pk_mul_f32 v[20:21], v[20:21], v[212:213] op_sel_hi:[1,0]
	v_pk_mul_f32 v[22:23], v[22:23], v[212:213] op_sel_hi:[1,0]
	v_pk_mul_f32 v[24:25], v[24:25], v[212:213] op_sel_hi:[1,0]
	v_pk_mul_f32 v[26:27], v[26:27], v[212:213] op_sel_hi:[1,0]
	v_pk_mul_f32 v[16:17], v[16:17], v[212:213] op_sel_hi:[1,0]
	v_pk_mul_f32 v[18:19], v[18:19], v[212:213] op_sel_hi:[1,0]
	v_pk_mul_f32 v[174:175], v[28:29], s[90:91] op_sel_hi:[1,0]
	v_pk_mul_f32 v[176:177], v[30:31], s[90:91] op_sel_hi:[1,0]
	v_pk_mul_f32 v[178:179], v[20:21], s[90:91] op_sel_hi:[1,0]
	v_pk_mul_f32 v[180:181], v[22:23], s[90:91] op_sel_hi:[1,0]
	v_exp_f32_e32 v174, v174
	v_exp_f32_e32 v175, v175
	v_exp_f32_e32 v176, v176
	v_exp_f32_e32 v177, v177
	v_exp_f32_e32 v178, v178
	v_exp_f32_e32 v179, v179
	v_exp_f32_e32 v180, v180
	v_exp_f32_e32 v181, v181
	v_pk_add_f32 v[174:175], v[174:175], 1.0 op_sel_hi:[1,0]
	v_pk_add_f32 v[176:177], v[176:177], 1.0 op_sel_hi:[1,0]
	v_pk_add_f32 v[178:179], v[178:179], 1.0 op_sel_hi:[1,0]
	v_pk_add_f32 v[180:181], v[180:181], 1.0 op_sel_hi:[1,0]
	v_rcp_f32_e32 v174, v174
	v_rcp_f32_e32 v175, v175
	v_rcp_f32_e32 v176, v176
	v_rcp_f32_e32 v177, v177
	v_rcp_f32_e32 v178, v178
	v_rcp_f32_e32 v179, v179
	v_rcp_f32_e32 v180, v180
	v_rcp_f32_e32 v181, v181
	v_pk_mul_f32 v[28:29], v[28:29], v[174:175]
	v_pk_mul_f32 v[30:31], v[30:31], v[176:177]
	v_pk_mul_f32 v[20:21], v[20:21], v[178:179]
	v_pk_mul_f32 v[22:23], v[22:23], v[180:181]
	v_pk_mul_f32 v[28:29], v[24:25], v[28:29]
	v_pk_mul_f32 v[30:31], v[26:27], v[30:31]
	v_pk_mul_f32 v[20:21], v[16:17], v[20:21]
	v_pk_mul_f32 v[22:23], v[18:19], v[22:23]
	v_cvt_pk_bf16_f32 v28, v28, v29
	v_cvt_pk_bf16_f32 v29, v30, v31
	v_cvt_pk_bf16_f32 v30, v20, v21
	v_cvt_pk_bf16_f32 v31, v22, v23
	s_nop 1
	v_permlane16_swap_b32 v28, v30
	v_permlane16_swap_b32 v29, v31
	global_store_dwordx4 v160, v[28:31], s[34:35] sc1
	v_pk_mul_f32 v[12:13], v[12:13], v[212:213] op_sel:[0,1] op_sel_hi:[1,1]
	v_pk_mul_f32 v[14:15], v[14:15], v[212:213] op_sel:[0,1] op_sel_hi:[1,1]
	v_pk_mul_f32 v[4:5], v[4:5], v[212:213] op_sel:[0,1] op_sel_hi:[1,1]
	v_pk_mul_f32 v[6:7], v[6:7], v[212:213] op_sel:[0,1] op_sel_hi:[1,1]
	v_pk_mul_f32 v[8:9], v[8:9], v[212:213] op_sel:[0,1] op_sel_hi:[1,1]
	v_pk_mul_f32 v[10:11], v[10:11], v[212:213] op_sel:[0,1] op_sel_hi:[1,1]
	v_pk_mul_f32 v[0:1], v[0:1], v[212:213] op_sel:[0,1] op_sel_hi:[1,1]
	v_pk_mul_f32 v[2:3], v[2:3], v[212:213] op_sel:[0,1] op_sel_hi:[1,1]
	v_pk_mul_f32 v[174:175], v[12:13], s[90:91] op_sel_hi:[1,0]
	v_pk_mul_f32 v[176:177], v[14:15], s[90:91] op_sel_hi:[1,0]
	v_pk_mul_f32 v[178:179], v[4:5], s[90:91] op_sel_hi:[1,0]
	v_pk_mul_f32 v[180:181], v[6:7], s[90:91] op_sel_hi:[1,0]
	v_exp_f32_e32 v174, v174
	v_exp_f32_e32 v175, v175
	v_exp_f32_e32 v176, v176
	v_exp_f32_e32 v177, v177
	v_exp_f32_e32 v178, v178
	v_exp_f32_e32 v179, v179
	v_exp_f32_e32 v180, v180
	v_exp_f32_e32 v181, v181
	v_pk_add_f32 v[174:175], v[174:175], 1.0 op_sel_hi:[1,0]
	v_pk_add_f32 v[176:177], v[176:177], 1.0 op_sel_hi:[1,0]
	v_pk_add_f32 v[178:179], v[178:179], 1.0 op_sel_hi:[1,0]
	v_pk_add_f32 v[180:181], v[180:181], 1.0 op_sel_hi:[1,0]
	v_rcp_f32_e32 v174, v174
	v_rcp_f32_e32 v175, v175
	v_rcp_f32_e32 v176, v176
	v_rcp_f32_e32 v177, v177
	v_rcp_f32_e32 v178, v178
	v_rcp_f32_e32 v179, v179
	v_rcp_f32_e32 v180, v180
	v_rcp_f32_e32 v181, v181
	v_pk_mul_f32 v[12:13], v[12:13], v[174:175]
	v_pk_mul_f32 v[14:15], v[14:15], v[176:177]
	v_pk_mul_f32 v[4:5], v[4:5], v[178:179]
	v_pk_mul_f32 v[6:7], v[6:7], v[180:181]
	v_pk_mul_f32 v[12:13], v[8:9], v[12:13]
	v_pk_mul_f32 v[14:15], v[10:11], v[14:15]
	v_pk_mul_f32 v[4:5], v[0:1], v[4:5]
	v_pk_mul_f32 v[6:7], v[2:3], v[6:7]
	v_cvt_pk_bf16_f32 v12, v12, v13
	v_cvt_pk_bf16_f32 v13, v14, v15
	v_cvt_pk_bf16_f32 v14, v4, v5
	v_cvt_pk_bf16_f32 v15, v6, v7
	s_nop 1
	v_permlane16_swap_b32 v12, v14
	v_permlane16_swap_b32 v13, v15
	global_store_dwordx4 v161, v[12:15], s[34:35] sc1
	s_andn2_b64 vcc, exec, s[6:7]
	s_mov_b64 s[6:7], -1
	s_cbranch_vccnz .LBB0_543
	s_andn2_b64 vcc, exec, s[14:15]
	s_cbranch_vccnz .LBB0_542
	s_barrier
	s_branch .LBB0_542
